# GU GEMM last half-round split into 128-row half-units across all WGs (second-A-half fragment reads, MFMAs and epilogue half skipped)
# baseline (speedup 1.0000x reference)
; #define PG8_STAGE(bufoff, gbase, voff) do { _Pragma("unroll") for (int _i = 0; _i < 2; ++_i) \
;         __builtin_amdgcn_global_load_lds((const unsigned*)((const char*)(gbase) + (voff)[_i]), (PG8_LAS unsigned*)(lds + (bufoff) + ldsw + _i * 8192), 16, 0, 0); } while (0)
; #define PG8_WAIT_V(n) asm volatile("s_waitcnt vmcnt(" #n ")" ::: "memory")
; #define PG8_BAR __builtin_amdgcn_s_barrier()
; template <class Epi, class Sched, bool ALIGN_EPI = false, bool SP2 = false, bool HALFM = false>
; __device__ __forceinline__ void gemm_phase(PG8_LAS unsigned char* lds, const Gemm g, const Sched& S, const Epi& E) {
;     ...
;         PG8_STAGE(PG8_SB(0, 0), cB, voffB); PG8_STAGE(PG8_SB(0, 1), cB + hstep, voffB); PG8_STAGE(PG8_SA(0, 0), cA, voffA); PG8_STAGE(PG8_SA(0, 1), cA + hstep, voffA);
;         if (wr == 1) PG8_BAR;
;         PG8_WAIT_V(2); PG8_BAR;
;         PG8_STAGE(PG8_SB(1, 0), cB + kstep, voffB); PG8_STAGE(PG8_SA(1, 0), cA + kstep, voffA); PG8_STAGE(PG8_SB(1, 1), cB + hstep + kstep, voffB);
;         PG8_WAIT_V(6); PG8_BAR;
.LBB0_172:
	v_readlane_b32 s22, v254, 5
	s_lshl_b32 s5, s5, 5
	v_mov_b32_e32 v131, v81
	v_readlane_b32 s23, v254, 6
	s_and_b32 s12, s5, 0x60
	s_add_i32 m0, s47, 0x18000
	v_lshl_add_u64 v[0:1], v[0:1], 0, s[82:83]
	v_lshl_add_u64 v[12:13], s[22:23], 0, v[130:131]
	v_mov_b32_e32 v133, v81
	s_lshl_b32 s9, s8, 13
	s_lshl_b32 s5, s12, 7
	global_load_lds_dwordx4 v[0:1], off
	v_lshl_add_u64 v[0:1], v[2:3], 0, s[82:83]
	s_add_i32 m0, s47, 0x1a000
	s_add_i32 s51, s47, 0x8000
	s_add_i32 s52, s47, 0xa000
	v_lshl_add_u64 v[14:15], s[22:23], 0, v[132:133]
	global_load_lds_dwordx4 v[0:1], off
	v_lshl_add_u64 v[0:1], v[12:13], 0, s[82:83]
	s_mov_b32 m0, s51
	s_add_u32 s10, s24, 0x40080
	global_load_lds_dwordx4 v[0:1], off
	v_lshl_add_u64 v[0:1], v[14:15], 0, s[82:83]
	s_mov_b32 m0, s52
	s_addc_u32 s11, s25, 0
	global_load_lds_dwordx4 v[0:1], off
	s_add_i32 m0, s47, 0x1c000
	v_lshl_add_u64 v[0:1], s[10:11], 0, v[80:81]
	global_load_lds_dwordx4 v[0:1], off
	v_lshl_add_u64 v[0:1], s[10:11], 0, v[134:135]
	s_add_i32 m0, s47, 0x1e000
	s_cmpk_lt_u32 s4, 0x100
	global_load_lds_dwordx4 v[0:1], off
	s_waitcnt vmcnt(8)
	s_barrier
	v_lshrrev_b32_e32 v1, 1, v4
	v_and_b32_e32 v1, 24, v1
	v_and_b32_e32 v0, 15, v4
	v_lshlrev_b32_e32 v2, 1, v1
	v_lshl_or_b32 v142, s8, 6, v0
	v_lshl_or_b32 v2, v0, 6, v2
	v_lshlrev_b32_e32 v0, 2, v0
	v_and_b32_e32 v3, 32, v0
	v_bitop3_b32 v143, v2, s5, v3 bitop3:0xde
	s_cselect_b64 s[4:5], -1, 0
	s_lshl_b32 s8, s8, 8
	s_add_i32 s8, s8, 0
	s_add_i32 s8, s8, 0x24900
	v_add_u32_e32 v145, s8, v0
	v_lshlrev_b32_e32 v0, 14, v5
	v_and_b32_e32 v0, 0xffff8000, v0
	v_or_b32_e32 v144, s12, v1
	v_lshl_add_u32 v0, v6, 11, v0
	v_and_b32_e32 v1, 1, v5
	v_lshl_or_b32 v0, v1, 6, v0
	v_lshl_add_u32 v136, v7, 1, v0
	v_lshlrev_b32_e32 v0, 14, v8
	v_and_b32_e32 v0, 0xffff8000, v0
	s_waitcnt vmcnt(6)
	v_lshl_add_u32 v0, v9, 11, v0
	v_and_b32_e32 v1, 1, v8
	v_bitop3_b32 v4, v2, s9, v3 bitop3:0xde
	v_lshl_or_b32 v0, v1, 6, v0
	v_readlane_b32 s8, v254, 2
	v_mov_b32_e32 v137, v81
	v_lshl_add_u32 v138, v10, 1, v0
	v_mov_b32_e32 v139, v81
	s_mov_b32 s55, 0
	v_add_u32_e32 v146, 0, v4
	v_readlane_b32 s56, v253, 63
	s_mov_b32 s57, s8
	s_mov_b32 s53, 0
	s_barrier
	v_readlane_b32 s9, v254, 3
	s_mov_b32 s99, 0
	s_mov_b32 s101, 0
	s_branch .LBB0_175

; #define PG8_STAGE(bufoff, gbase, voff) do { _Pragma("unroll") for (int _i = 0; _i < 2; ++_i) \
;         __builtin_amdgcn_global_load_lds((const unsigned*)((const char*)(gbase) + (voff)[_i]), (PG8_LAS unsigned*)(lds + (bufoff) + ldsw + _i * 8192), 16, 0, 0); } while (0)
; #define PG8_LDA(dst, b, h) do { _Pragma("unroll") for (int m = 0; m < 4; ++m) _Pragma("unroll") for (int k = 0; k < 2; ++k) dst[m][k] = *(const PG8_LAS bf16x8*)(lds + PG8_SA(b, h) + aoff + m * 2048 + k * 1024); } while (0)
; #define PG8_LDB(dst, b, h) do { _Pragma("unroll") for (int n = 0; n < 2; ++n) _Pragma("unroll") for (int k = 0; k < 2; ++k) dst[n][k] = *(const PG8_LAS bf16x8*)(lds + PG8_SB(b, h) + boff + n * 2048 + k * 1024); } while (0)
; #define PG8_MMA(ai, bj, At, Bt) do { __builtin_amdgcn_s_setprio(1); _Pragma("unroll") for (int m = 0; m < 4; ++m) _Pragma("unroll") for (int n = 0; n < 2; ++n) _Pragma("unroll") for (int k = 0; k < 2; ++k) \
;         acc[ai][bj][m][n] = __builtin_amdgcn_mfma_f32_16x16x32_bf16(Bt[n][k], At[m][k], acc[ai][bj][m][n], 0, 0, 0); __builtin_amdgcn_s_setprio(0); } while (0)
; #define PG8_WAIT_V(n) asm volatile("s_waitcnt vmcnt(" #n ")" ::: "memory")
; #define PG8_WAIT_L(n) asm volatile("s_waitcnt lgkmcnt(" #n ")" ::: "memory")
; #define PG8_BAR __builtin_amdgcn_s_barrier()
; #define PG8_SCHED __builtin_amdgcn_sched_barrier(0)
; template <class Epi, class Sched, bool ALIGN_EPI = false, bool SP2 = false, bool HALFM = false>
; __device__ __forceinline__ void gemm_phase(PG8_LAS unsigned char* lds, const Gemm g, const Sched& S, const Epi& E) {
;     ...
;             PG8_LDB(B0, 0, 0); PG8_LDB(B1, 0, 1); PG8_SCHED; PG8_LDA(At, 0, 0); PG8_STAGE(PG8_SA(1, 1), a1 + hstep, voffA);
;             PG8_WAIT_V(8); PG8_WAIT_L(0); PG8_BAR; PG8_MMA(0, 0, At, B0); PG8_MMA(0, 1, At, B1); PG8_BAR; PG8_SCHED;
;             if constexpr (!HALFM) PG8_LDA(At, 0, 1); PG8_STAGE(PG8_SB(0, 0), b2, voffB); PG8_STAGE(PG8_SB(0, 1), b2 + hstep, voffB); PG8_STAGE(PG8_SA(0, 0), a2, voffA);
;             PG8_WAIT_V(8); PG8_WAIT_L(0); PG8_BAR; if constexpr (!HALFM) { PG8_MMA(1, 0, At, B0); PG8_MMA(1, 1, At, B1); } PG8_BAR; PG8_SCHED;
.LBB0_179:
	s_add_u32 s26, s22, 0xfffc0080
	s_addc_u32 s27, s23, -1
	s_and_b64 s[24:25], s[24:25], exec
	s_cselect_b32 s27, s27, s11
	s_cselect_b32 s26, s26, s58
	s_cselect_b32 s25, s63, s9
	s_cselect_b32 s24, s62, s59
	s_add_i32 s65, 0, 0x10000
	v_add_u32_e32 v140, s65, v143
	s_add_i32 s68, 0, 0x14000
	ds_read_b128 v[148:151], v140
	ds_read_b128 v[160:163], v140 offset:1024
	ds_read_b128 v[164:167], v140 offset:2048
	ds_read_b128 v[168:171], v140 offset:3072
	v_add_u32_e32 v140, s68, v143
	ds_read_b128 v[172:175], v140
	ds_read_b128 v[176:179], v140 offset:1024
	ds_read_b128 v[180:183], v140 offset:2048
	ds_read_b128 v[184:187], v140 offset:3072
	v_lshl_add_u64 v[140:141], s[22:23], 0, v[136:137]
	s_add_i32 m0, s47, 0xc000
	ds_read_b128 v[202:205], v146
	ds_read_b128 v[206:209], v146 offset:1024
	ds_read_b128 v[210:213], v146 offset:2048
	ds_read_b128 v[214:217], v146 offset:3072
	ds_read_b128 v[218:221], v146 offset:4096
	ds_read_b128 v[222:225], v146 offset:5120
	ds_read_b128 v[226:229], v146 offset:6144
	ds_read_b128 v[230:233], v146 offset:7168
	global_load_lds_dwordx4 v[140:141], off
	v_lshl_add_u64 v[140:141], s[22:23], 0, v[138:139]
	s_add_i32 m0, s47, 0xe000
	s_nop 0
	global_load_lds_dwordx4 v[140:141], off
	s_waitcnt vmcnt(8)
	s_waitcnt lgkmcnt(0)
	s_setprio 1
	s_barrier
	v_mfma_f32_16x16x32_bf16 v[126:129], v[148:151], v[202:205], v[126:129]
	v_mfma_f32_16x16x32_bf16 v[122:125], v[164:167], v[202:205], v[122:125]
	v_mfma_f32_16x16x32_bf16 v[110:113], v[148:151], v[210:213], v[110:113]
	v_mfma_f32_16x16x32_bf16 v[106:109], v[164:167], v[210:213], v[106:109]
	v_mfma_f32_16x16x32_bf16 v[94:97], v[148:151], v[218:221], v[94:97]
	v_mfma_f32_16x16x32_bf16 v[90:93], v[164:167], v[218:221], v[90:93]
	v_mfma_f32_16x16x32_bf16 v[76:79], v[148:151], v[226:229], v[76:79]
	v_mfma_f32_16x16x32_bf16 v[72:75], v[164:167], v[226:229], v[72:75]
	v_mfma_f32_16x16x32_bf16 v[126:129], v[160:163], v[206:209], v[126:129]
	v_mfma_f32_16x16x32_bf16 v[122:125], v[168:171], v[206:209], v[122:125]
	v_mfma_f32_16x16x32_bf16 v[110:113], v[160:163], v[214:217], v[110:113]
	v_mfma_f32_16x16x32_bf16 v[106:109], v[168:171], v[214:217], v[106:109]
	v_mfma_f32_16x16x32_bf16 v[94:97], v[160:163], v[222:225], v[94:97]
	v_mfma_f32_16x16x32_bf16 v[90:93], v[168:171], v[222:225], v[90:93]
	v_mfma_f32_16x16x32_bf16 v[76:79], v[160:163], v[230:233], v[76:79]
	v_mfma_f32_16x16x32_bf16 v[72:75], v[168:171], v[230:233], v[72:75]
	v_mfma_f32_16x16x32_bf16 v[118:121], v[172:175], v[202:205], v[118:121]
	v_mfma_f32_16x16x32_bf16 v[114:117], v[180:183], v[202:205], v[114:117]
	v_mfma_f32_16x16x32_bf16 v[102:105], v[172:175], v[210:213], v[102:105]
	v_mfma_f32_16x16x32_bf16 v[98:101], v[180:183], v[210:213], v[98:101]
	v_mfma_f32_16x16x32_bf16 v[86:89], v[172:175], v[218:221], v[86:89]
	v_mfma_f32_16x16x32_bf16 v[82:85], v[180:183], v[218:221], v[82:85]
	v_mfma_f32_16x16x32_bf16 v[68:71], v[172:175], v[226:229], v[68:71]
	v_mfma_f32_16x16x32_bf16 v[64:67], v[180:183], v[226:229], v[64:67]
	v_mfma_f32_16x16x32_bf16 v[118:121], v[176:179], v[206:209], v[118:121]
	v_mfma_f32_16x16x32_bf16 v[114:117], v[184:187], v[206:209], v[114:117]
	v_mfma_f32_16x16x32_bf16 v[102:105], v[176:179], v[214:217], v[102:105]
	v_mfma_f32_16x16x32_bf16 v[98:101], v[184:187], v[214:217], v[98:101]
	v_mfma_f32_16x16x32_bf16 v[86:89], v[176:179], v[222:225], v[86:89]
	v_mfma_f32_16x16x32_bf16 v[82:85], v[184:187], v[222:225], v[82:85]
	v_mfma_f32_16x16x32_bf16 v[68:71], v[176:179], v[230:233], v[68:71]
	v_mfma_f32_16x16x32_bf16 v[64:67], v[184:187], v[230:233], v[64:67]
	s_barrier
	s_setprio 0
	s_add_i32 s65, s65, s46
	v_lshl_add_u64 v[140:141], s[24:25], 0, v[80:81]
	s_mov_b32 m0, s65
	s_cmp_lg_u32 s99, 0
	s_cbranch_scc1 .Lgu_half_rdskip0
	ds_read_b128 v[202:205], v146 offset:16384
	ds_read_b128 v[206:209], v146 offset:17408
	ds_read_b128 v[210:213], v146 offset:18432
	ds_read_b128 v[214:217], v146 offset:19456
	ds_read_b128 v[218:221], v146 offset:20480
	ds_read_b128 v[222:225], v146 offset:21504
	ds_read_b128 v[226:229], v146 offset:22528
	ds_read_b128 v[230:233], v146 offset:23552
.Lgu_half_rdskip0:
	global_load_lds_dwordx4 v[140:141], off
	s_add_i32 m0, s65, 0x2000
	s_add_u32 s66, s24, 0x40000
	v_lshl_add_u64 v[152:153], s[24:25], 0, v[134:135]
	s_addc_u32 s67, s25, 0
	s_add_i32 s65, s68, s46
	global_load_lds_dwordx4 v[152:153], off
	v_lshl_add_u64 v[188:189], s[66:67], 0, v[80:81]
	s_mov_b32 m0, s65
	v_lshl_add_u64 v[196:197], s[26:27], 0, v[132:133]
	global_load_lds_dwordx4 v[188:189], off
	v_lshl_add_u64 v[188:189], s[66:67], 0, v[134:135]
	s_add_i32 m0, s65, 0x2000
	s_nop 0
	global_load_lds_dwordx4 v[188:189], off
	v_lshl_add_u64 v[188:189], s[26:27], 0, v[130:131]
	s_mov_b32 m0, s47
	s_nop 0
	global_load_lds_dwordx4 v[188:189], off
	s_mov_b32 m0, s48
	s_nop 0
	global_load_lds_dwordx4 v[196:197], off
	s_waitcnt vmcnt(8)
	s_waitcnt lgkmcnt(0)
	s_setprio 1
	s_barrier
	s_cmp_lg_u32 s99, 0
	s_cbranch_scc1 .Lgu_half_skip0
; #define PG8_STAGE(bufoff, gbase, voff) do { _Pragma("unroll") for (int _i = 0; _i < 2; ++_i) \
;         __builtin_amdgcn_global_load_lds((const unsigned*)((const char*)(gbase) + (voff)[_i]), (PG8_LAS unsigned*)(lds + (bufoff) + ldsw + _i * 8192), 16, 0, 0); } while (0)
; #define PG8_LDA(dst, b, h) do { _Pragma("unroll") for (int m = 0; m < 4; ++m) _Pragma("unroll") for (int k = 0; k < 2; ++k) dst[m][k] = *(const PG8_LAS bf16x8*)(lds + PG8_SA(b, h) + aoff + m * 2048 + k * 1024); } while (0)
; #define PG8_LDB(dst, b, h) do { _Pragma("unroll") for (int n = 0; n < 2; ++n) _Pragma("unroll") for (int k = 0; k < 2; ++k) dst[n][k] = *(const PG8_LAS bf16x8*)(lds + PG8_SB(b, h) + boff + n * 2048 + k * 1024); } while (0)
; #define PG8_MMA(ai, bj, At, Bt) do { __builtin_amdgcn_s_setprio(1); _Pragma("unroll") for (int m = 0; m < 4; ++m) _Pragma("unroll") for (int n = 0; n < 2; ++n) _Pragma("unroll") for (int k = 0; k < 2; ++k) \
;         acc[ai][bj][m][n] = __builtin_amdgcn_mfma_f32_16x16x32_bf16(Bt[n][k], At[m][k], acc[ai][bj][m][n], 0, 0, 0); __builtin_amdgcn_s_setprio(0); } while (0)
; #define PG8_WAIT_V(n) asm volatile("s_waitcnt vmcnt(" #n ")" ::: "memory")
; #define PG8_WAIT_L(n) asm volatile("s_waitcnt lgkmcnt(" #n ")" ::: "memory")
; #define PG8_BAR __builtin_amdgcn_s_barrier()
; #define PG8_SCHED __builtin_amdgcn_sched_barrier(0)
; template <class Epi, class Sched, bool ALIGN_EPI = false, bool SP2 = false, bool HALFM = false>
; __device__ __forceinline__ void gemm_phase(PG8_LAS unsigned char* lds, const Gemm g, const Sched& S, const Epi& E) {
;     ...
;             PG8_WAIT_V(8); PG8_WAIT_L(0); PG8_BAR; if constexpr (!HALFM) { PG8_MMA(1, 0, At, B0); PG8_MMA(1, 1, At, B1); } PG8_BAR; PG8_SCHED;
;             PG8_LDB(B0, 1, 0); PG8_LDB(B1, 1, 1); PG8_SCHED; PG8_LDA(At, 1, 0); PG8_STAGE(PG8_SA(0, 1), a2 + hstep, voffA);
;             PG8_WAIT_V(8); PG8_WAIT_L(0); PG8_BAR; PG8_MMA(0, 0, At, B0); PG8_MMA(0, 1, At, B1); PG8_BAR; PG8_SCHED;
;             if constexpr (!HALFM) PG8_LDA(At, 1, 1); PG8_STAGE(PG8_SB(1, 0), b3, voffB); PG8_STAGE(PG8_SB(1, 1), b3 + hstep, voffB); PG8_STAGE(PG8_SA(1, 0), a3, voffA);
	v_mfma_f32_16x16x32_bf16 v[60:63], v[148:151], v[202:205], v[60:63]
	v_mfma_f32_16x16x32_bf16 v[56:59], v[164:167], v[202:205], v[56:59]
	v_mfma_f32_16x16x32_bf16 v[44:47], v[148:151], v[210:213], v[44:47]
	v_mfma_f32_16x16x32_bf16 v[40:43], v[164:167], v[210:213], v[40:43]
	v_mfma_f32_16x16x32_bf16 v[28:31], v[148:151], v[218:221], v[28:31]
	v_mfma_f32_16x16x32_bf16 v[24:27], v[164:167], v[218:221], v[24:27]
	v_mfma_f32_16x16x32_bf16 v[12:15], v[148:151], v[226:229], v[12:15]
	v_mfma_f32_16x16x32_bf16 v[8:11], v[164:167], v[226:229], v[8:11]
	v_mfma_f32_16x16x32_bf16 v[60:63], v[160:163], v[206:209], v[60:63]
	v_mfma_f32_16x16x32_bf16 v[56:59], v[168:171], v[206:209], v[56:59]
	v_mfma_f32_16x16x32_bf16 v[44:47], v[160:163], v[214:217], v[44:47]
	v_mfma_f32_16x16x32_bf16 v[40:43], v[168:171], v[214:217], v[40:43]
	v_mfma_f32_16x16x32_bf16 v[28:31], v[160:163], v[222:225], v[28:31]
	v_mfma_f32_16x16x32_bf16 v[24:27], v[168:171], v[222:225], v[24:27]
	v_mfma_f32_16x16x32_bf16 v[12:15], v[160:163], v[230:233], v[12:15]
	v_mfma_f32_16x16x32_bf16 v[8:11], v[168:171], v[230:233], v[8:11]
	v_mfma_f32_16x16x32_bf16 v[52:55], v[172:175], v[202:205], v[52:55]
	v_mfma_f32_16x16x32_bf16 v[48:51], v[180:183], v[202:205], v[48:51]
	v_mfma_f32_16x16x32_bf16 v[36:39], v[172:175], v[210:213], v[36:39]
	v_mfma_f32_16x16x32_bf16 v[32:35], v[180:183], v[210:213], v[32:35]
	v_mfma_f32_16x16x32_bf16 v[20:23], v[172:175], v[218:221], v[20:23]
	v_mfma_f32_16x16x32_bf16 v[16:19], v[180:183], v[218:221], v[16:19]
	v_mfma_f32_16x16x32_bf16 v[4:7], v[172:175], v[226:229], v[4:7]
	v_mfma_f32_16x16x32_bf16 v[0:3], v[180:183], v[226:229], v[0:3]
	v_mfma_f32_16x16x32_bf16 v[52:55], v[176:179], v[206:209], v[52:55]
	v_mfma_f32_16x16x32_bf16 v[48:51], v[184:187], v[206:209], v[48:51]
	v_mfma_f32_16x16x32_bf16 v[36:39], v[176:179], v[214:217], v[36:39]
	v_mfma_f32_16x16x32_bf16 v[32:35], v[184:187], v[214:217], v[32:35]
	v_mfma_f32_16x16x32_bf16 v[20:23], v[176:179], v[222:225], v[20:23]
	v_mfma_f32_16x16x32_bf16 v[16:19], v[184:187], v[222:225], v[16:19]
	v_mfma_f32_16x16x32_bf16 v[4:7], v[176:179], v[230:233], v[4:7]
	v_mfma_f32_16x16x32_bf16 v[0:3], v[184:187], v[230:233], v[0:3]
.Lgu_half_skip0:
	s_barrier
	s_setprio 0
	s_add_i32 s65, 0, 0x18000
	v_add_u32_e32 v147, s65, v143
	s_add_i32 s66, 0, 0x1c000
	ds_read_b128 v[148:151], v147
	ds_read_b128 v[160:163], v147 offset:1024
	ds_read_b128 v[164:167], v147 offset:2048
	ds_read_b128 v[168:171], v147 offset:3072
	v_add_u32_e32 v147, s66, v143
	ds_read_b128 v[172:175], v147
	ds_read_b128 v[176:179], v147 offset:1024
	ds_read_b128 v[180:183], v147 offset:2048
	ds_read_b128 v[184:187], v147 offset:3072
	s_add_u32 s26, s26, 0x40000
	s_addc_u32 s27, s27, 0
	s_mov_b32 m0, s49
	v_lshl_add_u64 v[198:199], s[26:27], 0, v[130:131]
	ds_read_b128 v[202:205], v146 offset:32768
	ds_read_b128 v[206:209], v146 offset:33792
	ds_read_b128 v[210:213], v146 offset:34816
	ds_read_b128 v[214:217], v146 offset:35840
	ds_read_b128 v[218:221], v146 offset:36864
	ds_read_b128 v[222:225], v146 offset:37888
	ds_read_b128 v[226:229], v146 offset:38912
	ds_read_b128 v[230:233], v146 offset:39936
	global_load_lds_dwordx4 v[198:199], off
	v_lshl_add_u64 v[198:199], s[26:27], 0, v[132:133]
	s_mov_b32 m0, s50
	s_nop 0
	global_load_lds_dwordx4 v[198:199], off
	s_waitcnt vmcnt(8)
	s_waitcnt lgkmcnt(0)
	s_setprio 1
	s_barrier
	v_mfma_f32_16x16x32_bf16 v[126:129], v[148:151], v[202:205], v[126:129]
	v_mfma_f32_16x16x32_bf16 v[122:125], v[164:167], v[202:205], v[122:125]
	v_mfma_f32_16x16x32_bf16 v[110:113], v[148:151], v[210:213], v[110:113]
	v_mfma_f32_16x16x32_bf16 v[106:109], v[164:167], v[210:213], v[106:109]
	v_mfma_f32_16x16x32_bf16 v[94:97], v[148:151], v[218:221], v[94:97]
	v_mfma_f32_16x16x32_bf16 v[90:93], v[164:167], v[218:221], v[90:93]
	v_mfma_f32_16x16x32_bf16 v[76:79], v[148:151], v[226:229], v[76:79]
	v_mfma_f32_16x16x32_bf16 v[72:75], v[164:167], v[226:229], v[72:75]
	v_mfma_f32_16x16x32_bf16 v[126:129], v[160:163], v[206:209], v[126:129]
	v_mfma_f32_16x16x32_bf16 v[122:125], v[168:171], v[206:209], v[122:125]
	v_mfma_f32_16x16x32_bf16 v[110:113], v[160:163], v[214:217], v[110:113]
	v_mfma_f32_16x16x32_bf16 v[106:109], v[168:171], v[214:217], v[106:109]
	v_mfma_f32_16x16x32_bf16 v[94:97], v[160:163], v[222:225], v[94:97]
	v_mfma_f32_16x16x32_bf16 v[90:93], v[168:171], v[222:225], v[90:93]
	v_mfma_f32_16x16x32_bf16 v[76:79], v[160:163], v[230:233], v[76:79]
	v_mfma_f32_16x16x32_bf16 v[72:75], v[168:171], v[230:233], v[72:75]
	v_mfma_f32_16x16x32_bf16 v[118:121], v[172:175], v[202:205], v[118:121]
	v_mfma_f32_16x16x32_bf16 v[114:117], v[180:183], v[202:205], v[114:117]
	v_mfma_f32_16x16x32_bf16 v[102:105], v[172:175], v[210:213], v[102:105]
	v_mfma_f32_16x16x32_bf16 v[98:101], v[180:183], v[210:213], v[98:101]
	v_mfma_f32_16x16x32_bf16 v[86:89], v[172:175], v[218:221], v[86:89]
	v_mfma_f32_16x16x32_bf16 v[82:85], v[180:183], v[218:221], v[82:85]
	v_mfma_f32_16x16x32_bf16 v[68:71], v[172:175], v[226:229], v[68:71]
	v_mfma_f32_16x16x32_bf16 v[64:67], v[180:183], v[226:229], v[64:67]
	v_mfma_f32_16x16x32_bf16 v[118:121], v[176:179], v[206:209], v[118:121]
	v_mfma_f32_16x16x32_bf16 v[114:117], v[184:187], v[206:209], v[114:117]
	v_mfma_f32_16x16x32_bf16 v[102:105], v[176:179], v[214:217], v[102:105]
	v_mfma_f32_16x16x32_bf16 v[98:101], v[184:187], v[214:217], v[98:101]
	v_mfma_f32_16x16x32_bf16 v[86:89], v[176:179], v[222:225], v[86:89]
	v_mfma_f32_16x16x32_bf16 v[82:85], v[184:187], v[222:225], v[82:85]
	v_mfma_f32_16x16x32_bf16 v[68:71], v[176:179], v[230:233], v[68:71]
	v_mfma_f32_16x16x32_bf16 v[64:67], v[184:187], v[230:233], v[64:67]
	s_barrier
	s_setprio 0
	s_add_i32 s26, s65, s46
	v_lshl_add_u64 v[140:141], v[140:141], 0, s[82:83]
	s_mov_b32 m0, s26
	s_cmp_lg_u32 s99, 0
	s_cbranch_scc1 .Lgu_half_rdskip1
	ds_read_b128 v[202:205], v146 offset:49152
	ds_read_b128 v[206:209], v146 offset:50176
	ds_read_b128 v[210:213], v146 offset:51200
	ds_read_b128 v[214:217], v146 offset:52224
	ds_read_b128 v[218:221], v146 offset:53248
	ds_read_b128 v[222:225], v146 offset:54272
	ds_read_b128 v[226:229], v146 offset:55296
	ds_read_b128 v[230:233], v146 offset:56320
; #define PG8_STAGE(bufoff, gbase, voff) do { _Pragma("unroll") for (int _i = 0; _i < 2; ++_i) \
;         __builtin_amdgcn_global_load_lds((const unsigned*)((const char*)(gbase) + (voff)[_i]), (PG8_LAS unsigned*)(lds + (bufoff) + ldsw + _i * 8192), 16, 0, 0); } while (0)
; #define PG8_LDA(dst, b, h) do { _Pragma("unroll") for (int m = 0; m < 4; ++m) _Pragma("unroll") for (int k = 0; k < 2; ++k) dst[m][k] = *(const PG8_LAS bf16x8*)(lds + PG8_SA(b, h) + aoff + m * 2048 + k * 1024); } while (0)
; #define PG8_MMA(ai, bj, At, Bt) do { __builtin_amdgcn_s_setprio(1); _Pragma("unroll") for (int m = 0; m < 4; ++m) _Pragma("unroll") for (int n = 0; n < 2; ++n) _Pragma("unroll") for (int k = 0; k < 2; ++k) \
;         acc[ai][bj][m][n] = __builtin_amdgcn_mfma_f32_16x16x32_bf16(Bt[n][k], At[m][k], acc[ai][bj][m][n], 0, 0, 0); __builtin_amdgcn_s_setprio(0); } while (0)
; #define PG8_WAIT_V(n) asm volatile("s_waitcnt vmcnt(" #n ")" ::: "memory")
; #define PG8_WAIT_L(n) asm volatile("s_waitcnt lgkmcnt(" #n ")" ::: "memory")
; #define PG8_BAR __builtin_amdgcn_s_barrier()
; #define PG8_SCHED __builtin_amdgcn_sched_barrier(0)
; template <class Epi, class Sched, bool ALIGN_EPI = false, bool SP2 = false, bool HALFM = false>
; __device__ __forceinline__ void gemm_phase(PG8_LAS unsigned char* lds, const Gemm g, const Sched& S, const Epi& E) {
;     ...
;         for (int t = 0; t < nt; t += 2) {
;     ...
;             if constexpr (!HALFM) PG8_LDA(At, 1, 1); PG8_STAGE(PG8_SB(1, 0), b3, voffB); PG8_STAGE(PG8_SB(1, 1), b3 + hstep, voffB); PG8_STAGE(PG8_SA(1, 0), a3, voffA);
;             PG8_WAIT_V(8); PG8_WAIT_L(0); PG8_BAR; if constexpr (!HALFM) { PG8_MMA(1, 0, At, B0); PG8_MMA(1, 1, At, B1); } PG8_BAR; PG8_SCHED;
.Lgu_half_rdskip1:
	global_load_lds_dwordx4 v[140:141], off
	s_add_i32 m0, s26, 0x2000
	s_add_u32 s24, s24, 0x40080
	v_lshl_add_u64 v[140:141], v[152:153], 0, s[82:83]
	s_addc_u32 s25, s25, 0
	s_add_i32 s26, s66, s46
	global_load_lds_dwordx4 v[140:141], off
	v_lshl_add_u64 v[140:141], s[24:25], 0, v[80:81]
	s_mov_b32 m0, s26
	s_nop 0
	global_load_lds_dwordx4 v[140:141], off
	v_lshl_add_u64 v[140:141], s[24:25], 0, v[134:135]
	s_add_i32 m0, s26, 0x2000
	s_nop 0
	global_load_lds_dwordx4 v[140:141], off
	v_lshl_add_u64 v[140:141], v[188:189], 0, s[82:83]
	s_mov_b32 m0, s51
	s_nop 0
	global_load_lds_dwordx4 v[140:141], off
	v_lshl_add_u64 v[140:141], v[196:197], 0, s[82:83]
	s_mov_b32 m0, s52
	s_nop 0
	global_load_lds_dwordx4 v[140:141], off
	s_waitcnt vmcnt(8)
	s_waitcnt lgkmcnt(0)
	s_setprio 1
	s_barrier
	s_cmp_lg_u32 s99, 0
	s_cbranch_scc1 .Lgu_half_skip1
	v_mfma_f32_16x16x32_bf16 v[60:63], v[148:151], v[202:205], v[60:63]
	v_mfma_f32_16x16x32_bf16 v[56:59], v[164:167], v[202:205], v[56:59]
	v_mfma_f32_16x16x32_bf16 v[44:47], v[148:151], v[210:213], v[44:47]
	v_mfma_f32_16x16x32_bf16 v[40:43], v[164:167], v[210:213], v[40:43]
	v_mfma_f32_16x16x32_bf16 v[28:31], v[148:151], v[218:221], v[28:31]
	v_mfma_f32_16x16x32_bf16 v[24:27], v[164:167], v[218:221], v[24:27]
	v_mfma_f32_16x16x32_bf16 v[12:15], v[148:151], v[226:229], v[12:15]
	v_mfma_f32_16x16x32_bf16 v[8:11], v[164:167], v[226:229], v[8:11]
	v_mfma_f32_16x16x32_bf16 v[60:63], v[160:163], v[206:209], v[60:63]
	v_mfma_f32_16x16x32_bf16 v[56:59], v[168:171], v[206:209], v[56:59]
	v_mfma_f32_16x16x32_bf16 v[44:47], v[160:163], v[214:217], v[44:47]
	v_mfma_f32_16x16x32_bf16 v[40:43], v[168:171], v[214:217], v[40:43]
	v_mfma_f32_16x16x32_bf16 v[28:31], v[160:163], v[222:225], v[28:31]
	v_mfma_f32_16x16x32_bf16 v[24:27], v[168:171], v[222:225], v[24:27]
	v_mfma_f32_16x16x32_bf16 v[12:15], v[160:163], v[230:233], v[12:15]
	v_mfma_f32_16x16x32_bf16 v[8:11], v[168:171], v[230:233], v[8:11]
	v_mfma_f32_16x16x32_bf16 v[52:55], v[172:175], v[202:205], v[52:55]
	v_mfma_f32_16x16x32_bf16 v[48:51], v[180:183], v[202:205], v[48:51]
	v_mfma_f32_16x16x32_bf16 v[36:39], v[172:175], v[210:213], v[36:39]
	v_mfma_f32_16x16x32_bf16 v[32:35], v[180:183], v[210:213], v[32:35]
	v_mfma_f32_16x16x32_bf16 v[20:23], v[172:175], v[218:221], v[20:23]
	v_mfma_f32_16x16x32_bf16 v[16:19], v[180:183], v[218:221], v[16:19]
	v_mfma_f32_16x16x32_bf16 v[4:7], v[172:175], v[226:229], v[4:7]
	v_mfma_f32_16x16x32_bf16 v[0:3], v[180:183], v[226:229], v[0:3]
	v_mfma_f32_16x16x32_bf16 v[52:55], v[176:179], v[206:209], v[52:55]
	v_mfma_f32_16x16x32_bf16 v[48:51], v[184:187], v[206:209], v[48:51]
	v_mfma_f32_16x16x32_bf16 v[36:39], v[176:179], v[214:217], v[36:39]
	v_mfma_f32_16x16x32_bf16 v[32:35], v[184:187], v[214:217], v[32:35]
	v_mfma_f32_16x16x32_bf16 v[20:23], v[176:179], v[222:225], v[20:23]
	v_mfma_f32_16x16x32_bf16 v[16:19], v[184:187], v[222:225], v[16:19]
	v_mfma_f32_16x16x32_bf16 v[4:7], v[176:179], v[230:233], v[4:7]
	v_mfma_f32_16x16x32_bf16 v[0:3], v[184:187], v[230:233], v[0:3]
.Lgu_half_skip1:
	s_barrier
	s_setprio 0
	s_add_i32 s64, s64, 2
	s_add_u32 s22, s22, 0x100
	s_addc_u32 s23, s23, 0
	s_add_u32 s62, s62, 0x100
	s_addc_u32 s63, s63, 0
	s_cmp_gt_u32 s64, 13
	s_cbranch_scc1 .LBB0_183
